# v10 + rebalance W_D1 late conversions: P20 tail 86->54 tiles per WG, P13 idle tail takes 19 extra tiles per WG
# speedup vs baseline: 1.0030x; 1.0023x over previous
.LBB0_1301:
	s_and_b64 vcc, exec, s[6:7]
	s_cbranch_vccz .LBB0_1314
	s_cmp_lt_i32 s76, 32
	s_cbranch_scc1 .LBB0_1314
	s_mul_i32 s2, s76, 43
	s_add_i32 s3, s2, 0x3b20
	s_addk_i32 s2, 0x3b4b
	s_min_i32 s2, s2, 0x6600
	s_cmp_ge_i32 s3, s2
	s_cbranch_scc1 .LBB0_1314
	s_mov_b32 s99, s2
	s_mul_i32 s100, s76, 19
	s_addk_i32 s100, 0x7ea0
	s_add_i32 s2, s100, 19
	s_min_i32 s2, s2, 0x9100
	s_cmp_lt_i32 s100, s2
	s_cbranch_scc1 .Lrb_ok
	s_mov_b32 s2, s99
	s_mov_b32 s99, -1
.Lrb_ok:
	s_cmpk_gt_i32 s3, 0xfff
	s_cselect_b64 s[6:7], -1, 0
	s_and_b64 s[8:9], s[6:7], exec
	s_movk_i32 s12, 0x2dc
	s_cselect_b32 s16, s12, 0x2b4
	s_movk_i32 s12, 0x2e0
	s_cselect_b32 s8, 0xfffff000, 0
	s_movk_i32 s9, 0x2c0
	s_movk_i32 s10, 0x2d0
	s_movk_i32 s11, 0x2d8
	s_cselect_b32 s18, s12, 0x2b8
	s_movk_i32 s12, 0x2e4
	s_cselect_b32 s9, s9, 0x298
	s_cselect_b32 s10, s10, 0x2a8
	s_cselect_b32 s11, s11, 0x2b0
	s_cselect_b32 s19, s12, 0x2bc
	s_add_i32 s20, s8, s3
	s_add_u32 s14, s0, s9
	s_addc_u32 s15, s1, 0
	s_add_u32 s12, s0, s10
	s_addc_u32 s13, s1, 0
	s_add_u32 s10, s0, s11
	s_addc_u32 s11, s1, 0
	s_add_u32 s16, s0, s16
	s_addc_u32 s17, s1, 0
	s_add_u32 s8, s0, s18
	s_addc_u32 s9, s1, 0
	s_waitcnt vmcnt(0)
	s_barrier
	s_load_dword s18, s[8:9], 0x0
	s_add_u32 s8, s0, s19
	s_addc_u32 s9, s1, 0
	s_load_dword s19, s[8:9], 0x0
	s_waitcnt lgkmcnt(0)
	s_ashr_i32 s21, s18, 6
	s_abs_i32 s22, s21
	v_cvt_f32_u32_e32 v2, s22
	s_load_dwordx2 s[8:9], s[14:15], 0x0
	s_load_dword s18, s[16:17], 0x0
	s_sub_i32 s16, 0, s22
	s_abs_i32 s15, s20
	v_rcp_iflag_f32_e32 v2, v2
	s_xor_b32 s14, s20, s21
	s_ashr_i32 s14, s14, 31
	v_mul_f32_e32 v2, 0x4f7ffffe, v2
	v_cvt_u32_f32_e32 v2, v2
	s_nop 0
	v_readfirstlane_b32 s17, v2
	s_mul_i32 s16, s16, s17
	s_mul_hi_u32 s16, s17, s16
	s_add_i32 s17, s17, s16
	s_mul_hi_u32 s16, s15, s17
	s_mul_i32 s17, s16, s22
	s_sub_i32 s15, s15, s17
	s_add_i32 s17, s16, 1
	s_sub_i32 s23, s15, s22
	s_cmp_ge_u32 s15, s22
	s_cselect_b32 s16, s17, s16
	s_cselect_b32 s15, s23, s15
	s_add_i32 s17, s16, 1
	s_cmp_ge_u32 s15, s22
	s_cselect_b32 s15, s17, s16
	s_xor_b32 s15, s15, s14
	s_sub_i32 s15, s15, s14
	s_mul_i32 s14, s15, s21
	s_sub_i32 s16, s20, s14
	s_lshl_b32 s22, s16, 6
	s_cmp_lg_u32 s19, 1
	s_mov_b32 s14, s22
	s_cbranch_scc1 .LBB0_1306
	s_lshl_b32 s14, s16, 5
	s_and_b32 s17, s16, 2
	s_and_b32 s14, s14, 0xffffff80
	s_and_b32 s16, s22, 64
	s_or_b32 s14, s14, s16
	s_movk_i32 s16, 0x2c8
	s_and_b64 s[6:7], s[6:7], exec
	s_cselect_b32 s6, s16, 0x2a0
	s_add_u32 s6, s0, s6
	s_addc_u32 s7, s1, 0
	s_load_dwordx2 s[6:7], s[6:7], 0x0
	s_cmp_eq_u32 s17, 0
	s_waitcnt lgkmcnt(0)
	s_cselect_b32 s9, s9, s7
	s_cselect_b32 s8, s8, s6

.LBB0_1310:
	s_mov_b32 s8, s3
	s_add_i32 s3, s3, 1
	s_cmp_eq_u32 s3, s99
	s_cselect_b32 s3, s100, s3
	s_cmp_ge_i32 s3, s2
	s_cselect_b64 s[14:15], -1, 0
	s_cmp_lt_i32 s3, s2
	s_cselect_b32 s8, s3, s8
	s_cmpk_lt_u32 s8, 0x6600
	s_cselect_b32 s9, 12, 13
	s_add_i32 s10, s8, 0xfffff000
	s_cmpk_lt_u32 s10, 0x5600
	s_cselect_b32 s10, 0xfffff000, s23
	s_cmpk_gt_i32 s8, 0xfff
	s_cselect_b32 s9, s9, 11
	s_cselect_b32 s10, s10, 0
	s_add_i32 s20, s10, s8
	s_mul_i32 s9, s9, 40
	s_add_u32 s16, s0, s9
	s_addc_u32 s17, s1, 0
	s_load_dwordx4 s[8:11], s[16:17], 0xf8
	s_load_dwordx2 s[18:19], s[16:17], 0xe0
	s_abs_i32 s24, s20
	s_waitcnt lgkmcnt(0)
	s_ashr_i32 s21, s10, 6
	s_abs_i32 s10, s21
	v_cvt_f32_u32_e32 v251, s10
	s_sub_i32 s26, 0, s10
	s_xor_b32 s25, s20, s21
	s_ashr_i32 s25, s25, 31
	v_rcp_iflag_f32_e32 v251, v251
	s_nop 0
	v_mul_f32_e32 v251, 0x4f7ffffe, v251
	v_cvt_u32_f32_e32 v251, v251
	s_nop 0
	v_readfirstlane_b32 s27, v251
	s_mul_i32 s26, s26, s27
	s_mul_hi_u32 s26, s27, s26
	s_add_i32 s27, s27, s26
	s_mul_hi_u32 s26, s24, s27
	s_mul_i32 s27, s26, s10
	s_sub_i32 s24, s24, s27
	s_add_i32 s28, s26, 1
	s_sub_i32 s27, s24, s10
	s_cmp_ge_u32 s24, s10
	s_cselect_b32 s26, s28, s26
	s_cselect_b32 s24, s27, s24
	s_add_i32 s27, s26, 1
	s_cmp_ge_u32 s24, s10
	s_cselect_b32 s10, s27, s26
	s_xor_b32 s10, s10, s25
	s_sub_i32 s10, s10, s25
	s_mul_i32 s21, s10, s21
	s_sub_i32 s21, s20, s21
	s_lshl_b32 s24, s21, 6
	s_cmp_lg_u32 s11, 1
	s_mov_b32 s20, s24
	s_cbranch_scc1 .LBB0_1312
	s_load_dwordx2 s[26:27], s[16:17], 0xe8
	s_lshl_b32 s20, s21, 5
	s_and_b32 s11, s21, 2
	s_and_b32 s20, s20, 0xffffff80
	s_and_b32 s21, s24, 64
	s_or_b32 s20, s20, s21
	s_cmp_eq_u32 s11, 0
	s_waitcnt lgkmcnt(0)
	s_cselect_b32 s19, s19, s27
	s_cselect_b32 s18, s18, s26

.LBB0_2281:
	s_cmpk_lt_i32 s76, 0x80
	s_cselect_b64 s[2:3], -1, 0
	s_cmpk_lg_i32 s80, 0x100
	s_cselect_b64 s[6:7], -1, 0
	s_or_b64 s[2:3], s[2:3], s[6:7]
	s_and_b64 vcc, exec, s[2:3]
	s_cbranch_vccnz .LBB0_2293
	s_mul_i32 s6, s76, 54
	s_add_i32 s3, s6, 0x4b00
	s_add_i32 s2, s6, 0x4b36
	s_cmp_ge_i32 s3, s2
	s_cbranch_scc1 .LBB0_2293
	s_load_dwordx4 s[8:11], s[0:1], 0x300
	s_load_dwordx2 s[12:13], s[0:1], 0x2e8
	s_add_i32 s14, s6, 0xffffe500
	s_sub_i32 s6, 0x1b00, s6
	s_max_i32 s6, s14, s6
	s_waitcnt lgkmcnt(0)
	s_ashr_i32 s7, s10, 6
	s_abs_i32 s10, s7
	v_cvt_f32_u32_e32 v2, s10
	s_sub_i32 s16, 0, s10
	s_xor_b32 s15, s14, s7
	s_ashr_i32 s15, s15, 31
	v_rcp_iflag_f32_e32 v2, v2
	s_waitcnt vmcnt(0)
	s_barrier
	v_mul_f32_e32 v2, 0x4f7ffffe, v2
	v_cvt_u32_f32_e32 v2, v2
	s_nop 0
	v_readfirstlane_b32 s17, v2
	s_mul_i32 s16, s16, s17
	s_mul_hi_u32 s16, s17, s16
	s_add_i32 s17, s17, s16
	s_mul_hi_u32 s16, s6, s17
	s_mul_i32 s17, s16, s10
	s_sub_i32 s6, s6, s17
	s_add_i32 s18, s16, 1
	s_sub_i32 s17, s6, s10
	s_cmp_ge_u32 s6, s10
	s_cselect_b32 s16, s18, s16
	s_cselect_b32 s6, s17, s6
	s_add_i32 s17, s16, 1
	s_cmp_ge_u32 s6, s10
	s_cselect_b32 s6, s17, s16
	s_xor_b32 s6, s6, s15
	s_sub_i32 s17, s6, s15
	s_mul_i32 s6, s17, s7
	s_sub_i32 s6, s14, s6
	s_lshl_b32 s24, s6, 6
	s_cmp_lg_u32 s11, 1
	s_mov_b32 s16, s24
	s_cbranch_scc1 .LBB0_2285
	s_and_b32 s10, s6, 2
	s_lshl_b32 s11, s6, 5
	s_load_dwordx2 s[6:7], s[0:1], 0x2f0
	s_and_b32 s11, s11, 0x7fffff80
	s_and_b32 s14, s24, 64
	s_or_b32 s16, s11, s14
	s_cmp_eq_u32 s10, 0
	s_waitcnt lgkmcnt(0)
	s_cselect_b32 s13, s13, s7
	s_cselect_b32 s12, s12, s6
